# w_in epilogue: RoPE table rows of the next row group requested one group ahead (staged in free VGPRs), counted vmcnt instead of full drain
# speedup vs baseline: 1.0183x; 1.0090x over previous
.LBB0_573:
	s_add_i32 s2, s47, -1
	s_and_b32 s0, s47, -2
	s_cmp_eq_u32 s0, 4
	s_cselect_b64 s[0:1], -1, 0
	s_cmp_lt_u32 s2, 2
	s_cselect_b64 s[2:3], -1, 0
	s_or_b64 s[0:1], s[2:3], s[0:1]
	s_and_b64 s[30:31], s[20:21], s[0:1]
	s_waitcnt lgkmcnt(0)
	v_pk_mul_f32 v[132:133], v[132:133], v[170:171] op_sel_hi:[1,0]
	v_pk_mul_f32 v[130:131], v[130:131], v[170:171] op_sel_hi:[1,0]
	v_pk_mul_f32 v[128:129], v[128:129], v[170:171] op_sel_hi:[1,0]
	v_pk_mul_f32 v[126:127], v[126:127], v[170:171] op_sel_hi:[1,0]
	v_pk_mul_f32 v[124:125], v[124:125], v[170:171] op_sel_hi:[1,0]
	v_pk_mul_f32 v[122:123], v[122:123], v[170:171] op_sel_hi:[1,0]
	v_pk_mul_f32 v[120:121], v[120:121], v[170:171] op_sel_hi:[1,0]
	v_pk_mul_f32 v[118:119], v[118:119], v[170:171] op_sel_hi:[1,0]
	s_and_b64 vcc, exec, s[30:31]
	s_mov_b32 s54, 0xff800000
	s_cbranch_vccz .LBB0_577
	ds_bpermute_b32 v170, v192, v130
	ds_bpermute_b32 v171, v192, v131
	ds_bpermute_b32 v136, v192, v132
	ds_bpermute_b32 v137, v192, v133
	ds_bpermute_b32 v174, v192, v126
	ds_bpermute_b32 v175, v192, v127
	ds_bpermute_b32 v172, v192, v128
	ds_bpermute_b32 v173, v192, v129
	ds_bpermute_b32 v184, v192, v122
	ds_bpermute_b32 v185, v192, v123
	ds_bpermute_b32 v182, v192, v124
	ds_bpermute_b32 v183, v192, v125
	ds_bpermute_b32 v186, v192, v118
	ds_bpermute_b32 v187, v192, v119
	ds_bpermute_b32 v188, v192, v120
	ds_bpermute_b32 v189, v192, v121
	s_and_saveexec_b64 s[0:1], s[6:7]
	s_cbranch_execz .LBB0_576
	v_lshlrev_b64 v[190:191], 6, v[150:151]
	v_lshl_add_u64 v[190:191], s[72:73], 0, v[190:191]
	global_load_dwordx4 v[202:205], v[190:191], off
	global_load_dwordx4 v[206:209], v[190:191], off offset:32
	global_load_dwordx4 v[210:213], v[190:191], off offset:16
	global_load_dwordx4 v[214:217], v[190:191], off offset:48
	v_mov_b64_e32 v[234:235], v[190:191]
	global_load_dwordx4 v[218:221], v[234:235], off offset:1024
	global_load_dwordx4 v[222:225], v[234:235], off offset:1056
	global_load_dwordx4 v[226:229], v[234:235], off offset:1040
	global_load_dwordx4 v[230:233], v[234:235], off offset:1072
	s_waitcnt vmcnt(4)
	v_xor_b32_e32 v135, 0x80000000, v214
	v_xor_b32_e32 v159, 0x80000000, v215
	v_xor_b32_e32 v161, 0x80000000, v216
	v_xor_b32_e32 v163, 0x80000000, v217
	v_cndmask_b32_e64 v191, v217, v163, s[4:5]
	v_cndmask_b32_e64 v190, v216, v161, s[4:5]
	v_cndmask_b32_e64 v215, v215, v159, s[4:5]
	v_cndmask_b32_e64 v214, v214, v135, s[4:5]
	s_waitcnt lgkmcnt(2)
	v_pk_mul_f32 v[186:187], v[214:215], v[186:187]
	s_waitcnt lgkmcnt(0)
	v_pk_mul_f32 v[188:189], v[190:191], v[188:189]
	v_xor_b32_e32 v135, 0x80000000, v206
	v_xor_b32_e32 v159, 0x80000000, v207
	v_xor_b32_e32 v161, 0x80000000, v208
	v_xor_b32_e32 v163, 0x80000000, v209
	v_pk_fma_f32 v[120:121], v[120:121], v[212:213], v[188:189]
	v_pk_fma_f32 v[118:119], v[118:119], v[210:211], v[186:187]
	v_cndmask_b32_e64 v187, v209, v163, s[4:5]
	v_cndmask_b32_e64 v186, v208, v161, s[4:5]
	v_cndmask_b32_e64 v189, v207, v159, s[4:5]
	v_cndmask_b32_e64 v188, v206, v135, s[4:5]
	v_pk_mul_f32 v[184:185], v[188:189], v[184:185]
	v_pk_mul_f32 v[182:183], v[186:187], v[182:183]
	v_pk_mul_f32 v[174:175], v[214:215], v[174:175]
	v_pk_mul_f32 v[172:173], v[190:191], v[172:173]
	v_pk_mul_f32 v[170:171], v[188:189], v[170:171]
	v_pk_mul_f32 v[136:137], v[186:187], v[136:137]
	v_pk_fma_f32 v[124:125], v[124:125], v[204:205], v[182:183]
	v_pk_fma_f32 v[122:123], v[122:123], v[202:203], v[184:185]
	v_pk_fma_f32 v[128:129], v[128:129], v[212:213], v[172:173]
	v_pk_fma_f32 v[126:127], v[126:127], v[210:211], v[174:175]
	v_pk_fma_f32 v[132:133], v[132:133], v[204:205], v[136:137]
	v_pk_fma_f32 v[130:131], v[130:131], v[202:203], v[170:171]

.LBB0_577:
	s_cmp_eq_u32 s47, 1
	s_waitcnt lgkmcnt(0)
	v_lshl_or_b32 v170, s47, 8, v200
	s_cselect_b64 s[0:1], -1, 0
	s_cmp_eq_u32 s47, 4
	v_ashrrev_i32_e32 v171, 31, v170
	s_cselect_b64 s[2:3], -1, 0
	v_readlane_b32 s100, v255, 41
	v_readlane_b32 s101, v255, 42
	s_nop 1
	v_lshl_add_u64 v[170:171], v[170:171], 1, s[100:101]
	s_or_b64 vcc, s[0:1], s[2:3]
	v_mad_u64_u32 v[182:183], s[0:1], v150, s76, v[170:171]
	v_mov_b32_e32 v135, 0x3e38aa3b
	v_mov_b32_e32 v172, v183
	v_cndmask_b32_e32 v136, 1.0, v135, vcc
	v_mad_u64_u32 v[172:173], s[0:1], v151, s76, v[172:173]
	v_mov_b32_e32 v183, v172
	v_pk_mul_f32 v[174:175], v[136:137], v[132:133] op_sel_hi:[0,1]
	v_pk_mul_f32 v[172:173], v[136:137], v[130:131] op_sel_hi:[0,1]
	v_pk_mul_f32 v[184:185], v[136:137], v[128:129] op_sel_hi:[0,1]
	v_pk_mul_f32 v[186:187], v[136:137], v[126:127] op_sel_hi:[0,1]
	v_cvt_pk_bf16_f32 v172, v172, v173
	v_cvt_pk_bf16_f32 v173, v174, v175
	v_cvt_pk_bf16_f32 v174, v186, v187
	v_cvt_pk_bf16_f32 v175, v184, v185
	global_store_dwordx4 v[182:183], v[172:175], off
	v_pk_mul_f32 v[184:185], v[136:137], v[120:121] op_sel_hi:[0,1]
	v_pk_mul_f32 v[186:187], v[136:137], v[118:119] op_sel_hi:[0,1]
	v_pk_mul_f32 v[174:175], v[136:137], v[124:125] op_sel_hi:[0,1]
	v_pk_mul_f32 v[172:173], v[136:137], v[122:123] op_sel_hi:[0,1]
	v_cvt_pk_bf16_f32 v172, v172, v173
	v_cvt_pk_bf16_f32 v173, v174, v175
	v_cvt_pk_bf16_f32 v174, v186, v187
	v_cvt_pk_bf16_f32 v175, v184, v185
	global_store_dwordx4 v[182:183], v[172:175], off offset:256
	v_cndmask_b32_e64 v135, 0, 1, s[30:31]
	v_pk_mul_f32 v[116:117], v[116:117], v[168:169] op_sel_hi:[1,0]
	v_pk_mul_f32 v[114:115], v[114:115], v[168:169] op_sel_hi:[1,0]
	v_pk_mul_f32 v[112:113], v[112:113], v[168:169] op_sel_hi:[1,0]
	v_pk_mul_f32 v[110:111], v[110:111], v[168:169] op_sel_hi:[1,0]
	v_pk_mul_f32 v[108:109], v[108:109], v[168:169] op_sel_hi:[1,0]
	v_pk_mul_f32 v[106:107], v[106:107], v[168:169] op_sel_hi:[1,0]
	v_pk_mul_f32 v[104:105], v[104:105], v[168:169] op_sel_hi:[1,0]
	v_cmp_ne_u32_e64 s[0:1], 1, v135
	s_andn2_b64 vcc, exec, s[30:31]
	v_pk_mul_f32 v[102:103], v[102:103], v[168:169] op_sel_hi:[1,0]
	s_cbranch_vccnz .LBB0_581
	ds_bpermute_b32 v172, v192, v114
	ds_bpermute_b32 v173, v192, v115
	ds_bpermute_b32 v168, v192, v116
	ds_bpermute_b32 v169, v192, v117
	ds_bpermute_b32 v182, v192, v110
	ds_bpermute_b32 v183, v192, v111
	ds_bpermute_b32 v174, v192, v112
	ds_bpermute_b32 v175, v192, v113
	ds_bpermute_b32 v186, v192, v106
	ds_bpermute_b32 v187, v192, v107
	ds_bpermute_b32 v184, v192, v108
	ds_bpermute_b32 v185, v192, v109
	ds_bpermute_b32 v188, v192, v102
	ds_bpermute_b32 v189, v192, v103
	ds_bpermute_b32 v190, v192, v104
	ds_bpermute_b32 v191, v192, v105
	s_and_saveexec_b64 s[30:31], s[6:7]
	s_cbranch_execz .LBB0_580
	s_waitcnt vmcnt(2)
	v_mov_b64_e32 v[202:203], v[218:219]
	v_mov_b64_e32 v[204:205], v[220:221]
	v_mov_b64_e32 v[206:207], v[222:223]
	v_mov_b64_e32 v[208:209], v[224:225]
	v_mov_b64_e32 v[210:211], v[226:227]
	v_mov_b64_e32 v[212:213], v[228:229]
	v_mov_b64_e32 v[214:215], v[230:231]
	v_mov_b64_e32 v[216:217], v[232:233]
	global_load_dwordx4 v[218:221], v[234:235], off offset:2048
	global_load_dwordx4 v[222:225], v[234:235], off offset:2080
	global_load_dwordx4 v[226:229], v[234:235], off offset:2064
	global_load_dwordx4 v[230:233], v[234:235], off offset:2096
	v_xor_b32_e32 v135, 0x80000000, v214
	v_xor_b32_e32 v137, 0x80000000, v215
	v_xor_b32_e32 v151, 0x80000000, v216
	v_xor_b32_e32 v157, 0x80000000, v217
	v_cndmask_b32_e64 v217, v217, v157, s[4:5]
	v_cndmask_b32_e64 v216, v216, v151, s[4:5]
	v_cndmask_b32_e64 v215, v215, v137, s[4:5]
	v_cndmask_b32_e64 v214, v214, v135, s[4:5]
	s_waitcnt lgkmcnt(2)
	v_pk_mul_f32 v[188:189], v[214:215], v[188:189]
	s_waitcnt lgkmcnt(0)
	v_pk_mul_f32 v[190:191], v[216:217], v[190:191]
	v_xor_b32_e32 v135, 0x80000000, v206
	v_xor_b32_e32 v137, 0x80000000, v207
	v_xor_b32_e32 v151, 0x80000000, v208
	v_xor_b32_e32 v157, 0x80000000, v209
	v_pk_fma_f32 v[104:105], v[104:105], v[212:213], v[190:191]
	v_pk_fma_f32 v[102:103], v[102:103], v[210:211], v[188:189]
	v_cndmask_b32_e64 v189, v209, v157, s[4:5]
	v_cndmask_b32_e64 v188, v208, v151, s[4:5]
	v_cndmask_b32_e64 v191, v207, v137, s[4:5]
	v_cndmask_b32_e64 v190, v206, v135, s[4:5]
	v_pk_mul_f32 v[186:187], v[190:191], v[186:187]
	v_pk_mul_f32 v[184:185], v[188:189], v[184:185]
	v_pk_mul_f32 v[182:183], v[214:215], v[182:183]
	v_pk_mul_f32 v[174:175], v[216:217], v[174:175]
	v_pk_mul_f32 v[172:173], v[190:191], v[172:173]
	v_pk_mul_f32 v[168:169], v[188:189], v[168:169]
	v_pk_fma_f32 v[108:109], v[108:109], v[204:205], v[184:185]
	v_pk_fma_f32 v[106:107], v[106:107], v[202:203], v[186:187]
	v_pk_fma_f32 v[112:113], v[112:113], v[212:213], v[174:175]
	v_pk_fma_f32 v[110:111], v[110:111], v[210:211], v[182:183]
	v_pk_fma_f32 v[116:117], v[116:117], v[204:205], v[168:169]
	v_pk_fma_f32 v[114:115], v[114:115], v[202:203], v[172:173]

.LBB0_581:
	v_mov_b32_e32 v137, v136
	s_waitcnt lgkmcnt(0)
	v_mad_i64_i32 v[168:169], s[2:3], v156, s76, v[170:171]
	v_mov_b32_e32 v156, v136
	v_mov_b32_e32 v157, v136
	v_pk_mul_f32 v[174:175], v[156:157], v[116:117]
	v_pk_mul_f32 v[172:173], v[136:137], v[114:115]
	v_pk_mul_f32 v[182:183], v[156:157], v[112:113]
	v_pk_mul_f32 v[184:185], v[136:137], v[110:111]
	v_cvt_pk_bf16_f32 v172, v172, v173
	v_cvt_pk_bf16_f32 v173, v174, v175
	v_cvt_pk_bf16_f32 v174, v184, v185
	v_cvt_pk_bf16_f32 v175, v182, v183
	global_store_dwordx4 v[168:169], v[172:175], off
	v_pk_mul_f32 v[182:183], v[156:157], v[104:105]
	v_pk_mul_f32 v[184:185], v[136:137], v[102:103]
	v_pk_mul_f32 v[174:175], v[156:157], v[108:109]
	v_pk_mul_f32 v[172:173], v[136:137], v[106:107]
	v_pk_mul_f32 v[100:101], v[100:101], v[166:167] op_sel_hi:[1,0]
	v_cvt_pk_bf16_f32 v172, v172, v173
	v_cvt_pk_bf16_f32 v173, v174, v175
	v_cvt_pk_bf16_f32 v174, v184, v185
	v_cvt_pk_bf16_f32 v175, v182, v183
	global_store_dwordx4 v[168:169], v[172:175], off offset:256
	v_pk_mul_f32 v[98:99], v[98:99], v[166:167] op_sel_hi:[1,0]
	v_pk_mul_f32 v[96:97], v[96:97], v[166:167] op_sel_hi:[1,0]
	v_pk_mul_f32 v[94:95], v[94:95], v[166:167] op_sel_hi:[1,0]
	v_pk_mul_f32 v[92:93], v[92:93], v[166:167] op_sel_hi:[1,0]
	v_pk_mul_f32 v[90:91], v[90:91], v[166:167] op_sel_hi:[1,0]
	v_pk_mul_f32 v[88:89], v[88:89], v[166:167] op_sel_hi:[1,0]
	s_and_b64 vcc, exec, s[0:1]
	v_pk_mul_f32 v[86:87], v[86:87], v[166:167] op_sel_hi:[1,0]
	s_cbranch_vccnz .LBB0_585
	ds_bpermute_b32 v168, v192, v98
	ds_bpermute_b32 v169, v192, v99
	ds_bpermute_b32 v166, v192, v100
	ds_bpermute_b32 v167, v192, v101
	ds_bpermute_b32 v174, v192, v94
	ds_bpermute_b32 v175, v192, v95
	ds_bpermute_b32 v172, v192, v96
	ds_bpermute_b32 v173, v192, v97
	ds_bpermute_b32 v184, v192, v90
	ds_bpermute_b32 v185, v192, v91
	ds_bpermute_b32 v182, v192, v92
	ds_bpermute_b32 v183, v192, v93
	ds_bpermute_b32 v186, v192, v86
	ds_bpermute_b32 v187, v192, v87
	ds_bpermute_b32 v188, v192, v88
	ds_bpermute_b32 v189, v192, v89
	s_and_saveexec_b64 s[30:31], s[6:7]
	s_cbranch_execz .LBB0_584
	s_waitcnt vmcnt(2)
	v_mov_b64_e32 v[202:203], v[218:219]
	v_mov_b64_e32 v[204:205], v[220:221]
	v_mov_b64_e32 v[206:207], v[222:223]
	v_mov_b64_e32 v[208:209], v[224:225]
	v_mov_b64_e32 v[210:211], v[226:227]
	v_mov_b64_e32 v[212:213], v[228:229]
	v_mov_b64_e32 v[214:215], v[230:231]
	v_mov_b64_e32 v[216:217], v[232:233]
	global_load_dwordx4 v[218:221], v[234:235], off offset:3072
	global_load_dwordx4 v[222:225], v[234:235], off offset:3104
	global_load_dwordx4 v[226:229], v[234:235], off offset:3088
	global_load_dwordx4 v[230:233], v[234:235], off offset:3120
	v_xor_b32_e32 v135, 0x80000000, v214
	v_xor_b32_e32 v151, 0x80000000, v215
	v_xor_b32_e32 v155, 0x80000000, v216
	v_xor_b32_e32 v159, 0x80000000, v217
	v_cndmask_b32_e64 v191, v217, v159, s[4:5]
	v_cndmask_b32_e64 v190, v216, v155, s[4:5]
	v_cndmask_b32_e64 v215, v215, v151, s[4:5]
	v_cndmask_b32_e64 v214, v214, v135, s[4:5]
	s_waitcnt lgkmcnt(2)
	v_pk_mul_f32 v[186:187], v[214:215], v[186:187]
	s_waitcnt lgkmcnt(0)
	v_pk_mul_f32 v[188:189], v[190:191], v[188:189]
	v_xor_b32_e32 v135, 0x80000000, v206
	v_xor_b32_e32 v151, 0x80000000, v207
	v_xor_b32_e32 v155, 0x80000000, v208
	v_xor_b32_e32 v159, 0x80000000, v209
	v_pk_fma_f32 v[88:89], v[88:89], v[212:213], v[188:189]
	v_pk_fma_f32 v[86:87], v[86:87], v[210:211], v[186:187]
	v_cndmask_b32_e64 v187, v209, v159, s[4:5]
	v_cndmask_b32_e64 v186, v208, v155, s[4:5]
	v_cndmask_b32_e64 v189, v207, v151, s[4:5]
	v_cndmask_b32_e64 v188, v206, v135, s[4:5]
	v_pk_mul_f32 v[184:185], v[188:189], v[184:185]
	v_pk_mul_f32 v[182:183], v[186:187], v[182:183]
	v_pk_mul_f32 v[174:175], v[214:215], v[174:175]
	v_pk_mul_f32 v[172:173], v[190:191], v[172:173]
	v_pk_mul_f32 v[168:169], v[188:189], v[168:169]
	v_pk_mul_f32 v[166:167], v[186:187], v[166:167]
	v_pk_fma_f32 v[92:93], v[92:93], v[204:205], v[182:183]
	v_pk_fma_f32 v[90:91], v[90:91], v[202:203], v[184:185]
	v_pk_fma_f32 v[96:97], v[96:97], v[212:213], v[172:173]
	v_pk_fma_f32 v[94:95], v[94:95], v[210:211], v[174:175]
	v_pk_fma_f32 v[100:101], v[100:101], v[204:205], v[166:167]
	v_pk_fma_f32 v[98:99], v[98:99], v[202:203], v[168:169]

.LBB0_585:
	s_waitcnt lgkmcnt(0)
	v_mad_i64_i32 v[172:173], s[2:3], v154, s76, v[170:171]
	v_pk_mul_f32 v[154:155], v[156:157], v[100:101]
	v_pk_mul_f32 v[166:167], v[136:137], v[98:99]
	v_pk_mul_f32 v[174:175], v[156:157], v[96:97]
	v_pk_mul_f32 v[168:169], v[136:137], v[94:95]
	v_cvt_pk_bf16_f32 v166, v166, v167
	v_cvt_pk_bf16_f32 v167, v154, v155
	v_cvt_pk_bf16_f32 v168, v168, v169
	v_cvt_pk_bf16_f32 v169, v174, v175
	global_store_dwordx4 v[172:173], v[166:169], off
	v_pk_mul_f32 v[154:155], v[136:137], v[90:91]
	v_pk_mul_f32 v[84:85], v[84:85], v[160:161] op_sel_hi:[1,0]
	v_pk_mul_f32 v[166:167], v[156:157], v[92:93]
	v_pk_mul_f32 v[168:169], v[156:157], v[88:89]
	v_pk_mul_f32 v[156:157], v[136:137], v[86:87]
	v_cvt_pk_bf16_f32 v154, v154, v155
	v_cvt_pk_bf16_f32 v155, v166, v167
	v_cvt_pk_bf16_f32 v156, v156, v157
	v_cvt_pk_bf16_f32 v157, v168, v169
	global_store_dwordx4 v[172:173], v[154:157], off offset:256
	v_pk_mul_f32 v[82:83], v[82:83], v[160:161] op_sel_hi:[1,0]
	v_pk_mul_f32 v[80:81], v[80:81], v[160:161] op_sel_hi:[1,0]
	v_pk_mul_f32 v[78:79], v[78:79], v[160:161] op_sel_hi:[1,0]
	v_pk_mul_f32 v[76:77], v[76:77], v[160:161] op_sel_hi:[1,0]
	v_pk_mul_f32 v[74:75], v[74:75], v[160:161] op_sel_hi:[1,0]
	v_pk_mul_f32 v[72:73], v[72:73], v[160:161] op_sel_hi:[1,0]
	s_and_b64 vcc, exec, s[0:1]
	v_pk_mul_f32 v[70:71], v[70:71], v[160:161] op_sel_hi:[1,0]
	s_cbranch_vccnz .LBB0_589
	ds_bpermute_b32 v156, v192, v82
	ds_bpermute_b32 v157, v192, v83
	ds_bpermute_b32 v154, v192, v84
	ds_bpermute_b32 v155, v192, v85
	ds_bpermute_b32 v166, v192, v78
	ds_bpermute_b32 v167, v192, v79
	ds_bpermute_b32 v160, v192, v80
	ds_bpermute_b32 v161, v192, v81
	ds_bpermute_b32 v172, v192, v74
	ds_bpermute_b32 v173, v192, v75
	ds_bpermute_b32 v168, v192, v76
	ds_bpermute_b32 v169, v192, v77
	ds_bpermute_b32 v174, v192, v70
	ds_bpermute_b32 v175, v192, v71
	ds_bpermute_b32 v182, v192, v72
	ds_bpermute_b32 v183, v192, v73
	s_and_saveexec_b64 s[30:31], s[6:7]
	s_cbranch_execz .LBB0_588
	s_waitcnt vmcnt(2)
	v_mov_b64_e32 v[184:185], v[218:219]
	v_mov_b64_e32 v[186:187], v[220:221]
	v_mov_b64_e32 v[188:189], v[222:223]
	v_mov_b64_e32 v[190:191], v[224:225]
	v_mov_b64_e32 v[202:203], v[226:227]
	v_mov_b64_e32 v[204:205], v[228:229]
	v_mov_b64_e32 v[206:207], v[230:231]
	v_mov_b64_e32 v[208:209], v[232:233]
	s_mov_b64 s[100:101], 0x2000
	v_lshl_add_u64 v[234:235], v[234:235], 0, s[100:101]
	global_load_dwordx4 v[218:221], v[234:235], off offset:0
	global_load_dwordx4 v[222:225], v[234:235], off offset:32
	global_load_dwordx4 v[226:229], v[234:235], off offset:16
	global_load_dwordx4 v[230:233], v[234:235], off offset:48
	v_xor_b32_e32 v135, 0x80000000, v206
	v_xor_b32_e32 v151, 0x80000000, v207
	v_xor_b32_e32 v153, 0x80000000, v208
	v_xor_b32_e32 v159, 0x80000000, v209
	v_cndmask_b32_e64 v209, v209, v159, s[4:5]
	v_cndmask_b32_e64 v208, v208, v153, s[4:5]
	v_cndmask_b32_e64 v207, v207, v151, s[4:5]
	v_cndmask_b32_e64 v206, v206, v135, s[4:5]
	s_waitcnt lgkmcnt(2)
	v_pk_mul_f32 v[174:175], v[206:207], v[174:175]
	s_waitcnt lgkmcnt(0)
	v_pk_mul_f32 v[182:183], v[208:209], v[182:183]
	v_xor_b32_e32 v135, 0x80000000, v188
	v_xor_b32_e32 v151, 0x80000000, v189
	v_xor_b32_e32 v153, 0x80000000, v190
	v_xor_b32_e32 v159, 0x80000000, v191
	v_pk_fma_f32 v[72:73], v[72:73], v[204:205], v[182:183]
	v_pk_fma_f32 v[70:71], v[70:71], v[202:203], v[174:175]
	v_cndmask_b32_e64 v175, v191, v159, s[4:5]
	v_cndmask_b32_e64 v174, v190, v153, s[4:5]
	v_cndmask_b32_e64 v183, v189, v151, s[4:5]
	v_cndmask_b32_e64 v182, v188, v135, s[4:5]
	v_pk_mul_f32 v[172:173], v[182:183], v[172:173]
	v_pk_mul_f32 v[168:169], v[174:175], v[168:169]
	v_pk_mul_f32 v[166:167], v[206:207], v[166:167]
	v_pk_mul_f32 v[160:161], v[208:209], v[160:161]
	v_pk_mul_f32 v[156:157], v[182:183], v[156:157]
	v_pk_mul_f32 v[154:155], v[174:175], v[154:155]
	v_pk_fma_f32 v[76:77], v[76:77], v[186:187], v[168:169]
	v_pk_fma_f32 v[74:75], v[74:75], v[184:185], v[172:173]
	v_pk_fma_f32 v[80:81], v[80:81], v[204:205], v[160:161]
	v_pk_fma_f32 v[78:79], v[78:79], v[202:203], v[166:167]
	v_pk_fma_f32 v[84:85], v[84:85], v[186:187], v[154:155]
	v_pk_fma_f32 v[82:83], v[82:83], v[184:185], v[156:157]

.LBB0_589:
	s_waitcnt lgkmcnt(0)
	v_mad_i64_i32 v[160:161], s[2:3], v152, s76, v[170:171]
	v_mov_b32_e32 v152, v136
	v_mov_b32_e32 v153, v136
	v_pk_mul_f32 v[156:157], v[152:153], v[84:85]
	v_pk_mul_f32 v[154:155], v[136:137], v[82:83]
	v_pk_mul_f32 v[166:167], v[152:153], v[80:81]
	v_pk_mul_f32 v[168:169], v[136:137], v[78:79]
	v_cvt_pk_bf16_f32 v154, v154, v155
	v_cvt_pk_bf16_f32 v155, v156, v157
	v_cvt_pk_bf16_f32 v156, v168, v169
	v_cvt_pk_bf16_f32 v157, v166, v167
	global_store_dwordx4 v[160:161], v[154:157], off
	v_pk_mul_f32 v[166:167], v[152:153], v[72:73]
	v_pk_mul_f32 v[168:169], v[136:137], v[70:71]
	v_pk_mul_f32 v[156:157], v[152:153], v[76:77]
	v_pk_mul_f32 v[154:155], v[136:137], v[74:75]
	v_pk_mul_f32 v[68:69], v[68:69], v[158:159] op_sel_hi:[1,0]
	v_cvt_pk_bf16_f32 v154, v154, v155
	v_cvt_pk_bf16_f32 v155, v156, v157
	v_cvt_pk_bf16_f32 v156, v168, v169
	v_cvt_pk_bf16_f32 v157, v166, v167
	global_store_dwordx4 v[160:161], v[154:157], off offset:256
	v_pk_mul_f32 v[66:67], v[66:67], v[158:159] op_sel_hi:[1,0]
	v_pk_mul_f32 v[64:65], v[64:65], v[158:159] op_sel_hi:[1,0]
	v_add_u32_e32 v154, 0x80, v150
	v_pk_mul_f32 v[62:63], v[62:63], v[158:159] op_sel_hi:[1,0]
	v_pk_mul_f32 v[60:61], v[60:61], v[158:159] op_sel_hi:[1,0]
	v_pk_mul_f32 v[58:59], v[58:59], v[158:159] op_sel_hi:[1,0]
	v_pk_mul_f32 v[56:57], v[56:57], v[158:159] op_sel_hi:[1,0]
	v_pk_mul_f32 v[54:55], v[54:55], v[158:159] op_sel_hi:[1,0]
	s_and_b64 vcc, exec, s[0:1]
	v_ashrrev_i32_e32 v155, 31, v154
	s_cbranch_vccnz .LBB0_593
	ds_bpermute_b32 v158, v192, v66
	ds_bpermute_b32 v159, v192, v67
	ds_bpermute_b32 v156, v192, v68
	ds_bpermute_b32 v157, v192, v69
	ds_bpermute_b32 v166, v192, v62
	ds_bpermute_b32 v167, v192, v63
	ds_bpermute_b32 v160, v192, v64
	ds_bpermute_b32 v161, v192, v65
	ds_bpermute_b32 v172, v192, v58
	ds_bpermute_b32 v173, v192, v59
	ds_bpermute_b32 v168, v192, v60
	ds_bpermute_b32 v169, v192, v61
	ds_bpermute_b32 v174, v192, v54
	ds_bpermute_b32 v175, v192, v55
	ds_bpermute_b32 v182, v192, v56
	ds_bpermute_b32 v183, v192, v57
	s_and_saveexec_b64 s[30:31], s[6:7]
	s_cbranch_execz .LBB0_592
	s_waitcnt vmcnt(2)
	v_mov_b64_e32 v[184:185], v[218:219]
	v_mov_b64_e32 v[186:187], v[220:221]
	v_mov_b64_e32 v[188:189], v[222:223]
	v_mov_b64_e32 v[190:191], v[224:225]
	v_mov_b64_e32 v[202:203], v[226:227]
	v_mov_b64_e32 v[204:205], v[228:229]
	v_mov_b64_e32 v[206:207], v[230:231]
	v_mov_b64_e32 v[208:209], v[232:233]
	global_load_dwordx4 v[218:221], v[234:235], off offset:1024
	global_load_dwordx4 v[222:225], v[234:235], off offset:1056
	global_load_dwordx4 v[226:229], v[234:235], off offset:1040
	global_load_dwordx4 v[230:233], v[234:235], off offset:1072
	v_xor_b32_e32 v135, 0x80000000, v206
	v_xor_b32_e32 v151, 0x80000000, v207
	v_xor_b32_e32 v155, 0x80000000, v208
	v_xor_b32_e32 v163, 0x80000000, v209
	v_cndmask_b32_e64 v209, v209, v163, s[4:5]
	v_cndmask_b32_e64 v208, v208, v155, s[4:5]
	v_cndmask_b32_e64 v207, v207, v151, s[4:5]
	v_cndmask_b32_e64 v206, v206, v135, s[4:5]
	s_waitcnt lgkmcnt(2)
	v_pk_mul_f32 v[174:175], v[206:207], v[174:175]
	s_waitcnt lgkmcnt(0)
	v_pk_mul_f32 v[182:183], v[208:209], v[182:183]
	v_xor_b32_e32 v135, 0x80000000, v188
	v_xor_b32_e32 v151, 0x80000000, v189
	v_xor_b32_e32 v155, 0x80000000, v190
	v_xor_b32_e32 v163, 0x80000000, v191
	v_pk_fma_f32 v[56:57], v[56:57], v[204:205], v[182:183]
	v_pk_fma_f32 v[54:55], v[54:55], v[202:203], v[174:175]
	v_cndmask_b32_e64 v175, v191, v163, s[4:5]
	v_cndmask_b32_e64 v174, v190, v155, s[4:5]
	v_cndmask_b32_e64 v183, v189, v151, s[4:5]
	v_cndmask_b32_e64 v182, v188, v135, s[4:5]
	v_pk_mul_f32 v[172:173], v[182:183], v[172:173]
	v_pk_mul_f32 v[168:169], v[174:175], v[168:169]
	v_pk_mul_f32 v[166:167], v[206:207], v[166:167]
	v_pk_mul_f32 v[160:161], v[208:209], v[160:161]
	v_pk_mul_f32 v[158:159], v[182:183], v[158:159]
	v_pk_mul_f32 v[156:157], v[174:175], v[156:157]
	v_pk_fma_f32 v[60:61], v[60:61], v[186:187], v[168:169]
	v_pk_fma_f32 v[58:59], v[58:59], v[184:185], v[172:173]
	v_pk_fma_f32 v[64:65], v[64:65], v[204:205], v[160:161]
	v_pk_fma_f32 v[62:63], v[62:63], v[202:203], v[166:167]
	v_pk_fma_f32 v[68:69], v[68:69], v[186:187], v[156:157]
	v_pk_fma_f32 v[66:67], v[66:67], v[184:185], v[158:159]

.LBB0_593:
	s_waitcnt lgkmcnt(0)
	v_mad_i64_i32 v[158:159], s[2:3], v154, s76, v[170:171]
	v_pk_mul_f32 v[156:157], v[152:153], v[68:69]
	v_pk_mul_f32 v[154:155], v[136:137], v[66:67]
	v_pk_mul_f32 v[160:161], v[152:153], v[64:65]
	v_pk_mul_f32 v[166:167], v[136:137], v[62:63]
	v_cvt_pk_bf16_f32 v154, v154, v155
	v_cvt_pk_bf16_f32 v155, v156, v157
	v_cvt_pk_bf16_f32 v156, v166, v167
	v_cvt_pk_bf16_f32 v157, v160, v161
	global_store_dwordx4 v[158:159], v[154:157], off
	v_pk_mul_f32 v[160:161], v[152:153], v[56:57]
	v_pk_mul_f32 v[166:167], v[136:137], v[54:55]
	v_pk_mul_f32 v[154:155], v[152:153], v[60:61]
	v_pk_mul_f32 v[156:157], v[136:137], v[58:59]
	v_cvt_pk_bf16_f32 v153, v154, v155
	v_cvt_pk_bf16_f32 v152, v156, v157
	v_cvt_pk_bf16_f32 v154, v166, v167
	v_cvt_pk_bf16_f32 v155, v160, v161
	global_store_dwordx4 v[158:159], v[152:155], off offset:256
	v_pk_mul_f32 v[52:53], v[52:53], v[162:163] op_sel_hi:[1,0]
	v_pk_mul_f32 v[50:51], v[50:51], v[162:163] op_sel_hi:[1,0]
	v_add_u32_e32 v152, 0x90, v150
	v_pk_mul_f32 v[48:49], v[48:49], v[162:163] op_sel_hi:[1,0]
	v_pk_mul_f32 v[46:47], v[46:47], v[162:163] op_sel_hi:[1,0]
	v_pk_mul_f32 v[44:45], v[44:45], v[162:163] op_sel_hi:[1,0]
	v_pk_mul_f32 v[42:43], v[42:43], v[162:163] op_sel_hi:[1,0]
	v_pk_mul_f32 v[40:41], v[40:41], v[162:163] op_sel_hi:[1,0]
	v_pk_mul_f32 v[38:39], v[38:39], v[162:163] op_sel_hi:[1,0]
	s_and_b64 vcc, exec, s[0:1]
	v_ashrrev_i32_e32 v153, 31, v152
	s_cbranch_vccnz .LBB0_597
	ds_bpermute_b32 v156, v192, v50
	ds_bpermute_b32 v157, v192, v51
	ds_bpermute_b32 v154, v192, v52
	ds_bpermute_b32 v155, v192, v53
	ds_bpermute_b32 v160, v192, v46
	ds_bpermute_b32 v161, v192, v47
	ds_bpermute_b32 v158, v192, v48
	ds_bpermute_b32 v159, v192, v49
	ds_bpermute_b32 v166, v192, v42
	ds_bpermute_b32 v167, v192, v43
	ds_bpermute_b32 v162, v192, v44
	ds_bpermute_b32 v163, v192, v45
	ds_bpermute_b32 v168, v192, v38
	ds_bpermute_b32 v169, v192, v39
	ds_bpermute_b32 v172, v192, v40
	ds_bpermute_b32 v173, v192, v41
	s_and_saveexec_b64 s[30:31], s[6:7]
	s_cbranch_execz .LBB0_596
	s_waitcnt vmcnt(2)
	v_mov_b64_e32 v[182:183], v[218:219]
	v_mov_b64_e32 v[184:185], v[220:221]
	v_mov_b64_e32 v[186:187], v[222:223]
	v_mov_b64_e32 v[188:189], v[224:225]
	v_mov_b64_e32 v[202:203], v[226:227]
	v_mov_b64_e32 v[204:205], v[228:229]
	v_mov_b64_e32 v[206:207], v[230:231]
	v_mov_b64_e32 v[208:209], v[232:233]
	global_load_dwordx4 v[218:221], v[234:235], off offset:2048
	global_load_dwordx4 v[222:225], v[234:235], off offset:2080
	global_load_dwordx4 v[226:229], v[234:235], off offset:2064
	global_load_dwordx4 v[230:233], v[234:235], off offset:2096
	v_xor_b32_e32 v135, 0x80000000, v206
	v_xor_b32_e32 v151, 0x80000000, v207
	v_xor_b32_e32 v153, 0x80000000, v208
	v_xor_b32_e32 v165, 0x80000000, v209
	v_cndmask_b32_e64 v175, v209, v165, s[4:5]
	v_cndmask_b32_e64 v174, v208, v153, s[4:5]
	v_cndmask_b32_e64 v191, v207, v151, s[4:5]
	v_cndmask_b32_e64 v190, v206, v135, s[4:5]
	s_waitcnt lgkmcnt(2)
	v_pk_mul_f32 v[168:169], v[190:191], v[168:169]
	s_waitcnt lgkmcnt(0)
	v_pk_mul_f32 v[172:173], v[174:175], v[172:173]
	v_xor_b32_e32 v135, 0x80000000, v186
	v_xor_b32_e32 v151, 0x80000000, v187
	v_xor_b32_e32 v153, 0x80000000, v188
	v_xor_b32_e32 v165, 0x80000000, v189
	v_pk_fma_f32 v[40:41], v[40:41], v[204:205], v[172:173]
	v_pk_fma_f32 v[38:39], v[38:39], v[202:203], v[168:169]
	v_cndmask_b32_e64 v169, v189, v165, s[4:5]
	v_cndmask_b32_e64 v168, v188, v153, s[4:5]
	v_cndmask_b32_e64 v173, v187, v151, s[4:5]
	v_cndmask_b32_e64 v172, v186, v135, s[4:5]
	v_pk_mul_f32 v[166:167], v[172:173], v[166:167]
	v_pk_mul_f32 v[162:163], v[168:169], v[162:163]
	v_pk_mul_f32 v[160:161], v[190:191], v[160:161]
	v_pk_mul_f32 v[158:159], v[174:175], v[158:159]
	v_pk_mul_f32 v[156:157], v[172:173], v[156:157]
	v_pk_mul_f32 v[154:155], v[168:169], v[154:155]
	v_pk_fma_f32 v[44:45], v[44:45], v[184:185], v[162:163]
	v_pk_fma_f32 v[42:43], v[42:43], v[182:183], v[166:167]
	v_pk_fma_f32 v[48:49], v[48:49], v[204:205], v[158:159]
	v_pk_fma_f32 v[46:47], v[46:47], v[202:203], v[160:161]
	v_pk_fma_f32 v[52:53], v[52:53], v[184:185], v[154:155]
	v_pk_fma_f32 v[50:51], v[50:51], v[182:183], v[156:157]

.LBB0_597:
	s_waitcnt lgkmcnt(0)
	v_mad_i64_i32 v[158:159], s[2:3], v152, s76, v[170:171]
	v_mov_b32_e32 v152, v136
	v_mov_b32_e32 v153, v136
	v_pk_mul_f32 v[156:157], v[152:153], v[52:53]
	v_pk_mul_f32 v[154:155], v[136:137], v[50:51]
	v_pk_mul_f32 v[160:161], v[152:153], v[48:49]
	v_pk_mul_f32 v[162:163], v[136:137], v[46:47]
	v_cvt_pk_bf16_f32 v154, v154, v155
	v_cvt_pk_bf16_f32 v155, v156, v157
	v_cvt_pk_bf16_f32 v156, v162, v163
	v_cvt_pk_bf16_f32 v157, v160, v161
	global_store_dwordx4 v[158:159], v[154:157], off
	v_pk_mul_f32 v[160:161], v[152:153], v[40:41]
	v_pk_mul_f32 v[162:163], v[136:137], v[38:39]
	v_pk_mul_f32 v[156:157], v[152:153], v[44:45]
	v_pk_mul_f32 v[154:155], v[136:137], v[42:43]
	v_pk_mul_f32 v[36:37], v[36:37], v[164:165] op_sel_hi:[1,0]
	v_cvt_pk_bf16_f32 v154, v154, v155
	v_cvt_pk_bf16_f32 v155, v156, v157
	v_cvt_pk_bf16_f32 v156, v162, v163
	v_cvt_pk_bf16_f32 v157, v160, v161
	global_store_dwordx4 v[158:159], v[154:157], off offset:256
	v_pk_mul_f32 v[34:35], v[34:35], v[164:165] op_sel_hi:[1,0]
	v_pk_mul_f32 v[32:33], v[32:33], v[164:165] op_sel_hi:[1,0]
	v_add_u32_e32 v154, 0xa0, v150
	v_pk_mul_f32 v[30:31], v[30:31], v[164:165] op_sel_hi:[1,0]
	v_pk_mul_f32 v[28:29], v[28:29], v[164:165] op_sel_hi:[1,0]
	v_pk_mul_f32 v[26:27], v[26:27], v[164:165] op_sel_hi:[1,0]
	v_pk_mul_f32 v[24:25], v[24:25], v[164:165] op_sel_hi:[1,0]
	v_pk_mul_f32 v[22:23], v[22:23], v[164:165] op_sel_hi:[1,0]
	s_and_b64 vcc, exec, s[0:1]
	v_ashrrev_i32_e32 v155, 31, v154
	s_cbranch_vccnz .LBB0_601
	ds_bpermute_b32 v158, v192, v34
	ds_bpermute_b32 v159, v192, v35
	ds_bpermute_b32 v156, v192, v36
	ds_bpermute_b32 v157, v192, v37
	ds_bpermute_b32 v162, v192, v30
	ds_bpermute_b32 v163, v192, v31
	ds_bpermute_b32 v160, v192, v32
	ds_bpermute_b32 v161, v192, v33
	ds_bpermute_b32 v166, v192, v26
	ds_bpermute_b32 v167, v192, v27
	ds_bpermute_b32 v164, v192, v28
	ds_bpermute_b32 v165, v192, v29
	ds_bpermute_b32 v168, v192, v22
	ds_bpermute_b32 v169, v192, v23
	ds_bpermute_b32 v172, v192, v24
	ds_bpermute_b32 v173, v192, v25
	s_and_saveexec_b64 s[30:31], s[6:7]
	s_cbranch_execz .LBB0_600
	s_waitcnt vmcnt(2)
	v_mov_b64_e32 v[182:183], v[218:219]
	v_mov_b64_e32 v[184:185], v[220:221]
	v_mov_b64_e32 v[186:187], v[222:223]
	v_mov_b64_e32 v[188:189], v[224:225]
	v_mov_b64_e32 v[202:203], v[226:227]
	v_mov_b64_e32 v[204:205], v[228:229]
	v_mov_b64_e32 v[206:207], v[230:231]
	v_mov_b64_e32 v[208:209], v[232:233]
	global_load_dwordx4 v[218:221], v[234:235], off offset:3072
	global_load_dwordx4 v[222:225], v[234:235], off offset:3104
	global_load_dwordx4 v[226:229], v[234:235], off offset:3088
	global_load_dwordx4 v[230:233], v[234:235], off offset:3120
	v_xor_b32_e32 v135, 0x80000000, v206
	v_xor_b32_e32 v151, 0x80000000, v207
	v_xor_b32_e32 v155, 0x80000000, v208
	v_xor_b32_e32 v174, 0x80000000, v209
	v_cndmask_b32_e64 v191, v207, v151, s[4:5]
	v_cndmask_b32_e64 v190, v206, v135, s[4:5]
	v_cndmask_b32_e64 v175, v209, v174, s[4:5]
	v_cndmask_b32_e64 v174, v208, v155, s[4:5]
	s_waitcnt lgkmcnt(2)
	v_pk_mul_f32 v[168:169], v[190:191], v[168:169]
	s_waitcnt lgkmcnt(0)
	v_pk_mul_f32 v[172:173], v[174:175], v[172:173]
	v_pk_fma_f32 v[22:23], v[22:23], v[202:203], v[168:169]
	v_xor_b32_e32 v135, 0x80000000, v186
	v_xor_b32_e32 v151, 0x80000000, v187
	v_xor_b32_e32 v155, 0x80000000, v188
	v_xor_b32_e32 v168, 0x80000000, v189
	v_pk_fma_f32 v[24:25], v[24:25], v[204:205], v[172:173]
	v_cndmask_b32_e64 v169, v189, v168, s[4:5]
	v_cndmask_b32_e64 v168, v188, v155, s[4:5]
	v_cndmask_b32_e64 v173, v187, v151, s[4:5]
	v_cndmask_b32_e64 v172, v186, v135, s[4:5]
	v_pk_mul_f32 v[166:167], v[172:173], v[166:167]
	v_pk_mul_f32 v[164:165], v[168:169], v[164:165]
	v_pk_mul_f32 v[162:163], v[190:191], v[162:163]
	v_pk_mul_f32 v[160:161], v[174:175], v[160:161]
	v_pk_mul_f32 v[158:159], v[172:173], v[158:159]
	v_pk_mul_f32 v[156:157], v[168:169], v[156:157]
	v_pk_fma_f32 v[28:29], v[28:29], v[184:185], v[164:165]
	v_pk_fma_f32 v[26:27], v[26:27], v[182:183], v[166:167]
	v_pk_fma_f32 v[32:33], v[32:33], v[204:205], v[160:161]
	v_pk_fma_f32 v[30:31], v[30:31], v[202:203], v[162:163]
	v_pk_fma_f32 v[36:37], v[36:37], v[184:185], v[156:157]
	v_pk_fma_f32 v[34:35], v[34:35], v[182:183], v[158:159]

.LBB0_601:
	s_waitcnt lgkmcnt(0)
	v_mad_i64_i32 v[158:159], s[2:3], v154, s76, v[170:171]
	v_pk_mul_f32 v[156:157], v[152:153], v[36:37]
	v_pk_mul_f32 v[154:155], v[136:137], v[34:35]
	v_pk_mul_f32 v[160:161], v[152:153], v[32:33]
	v_pk_mul_f32 v[162:163], v[136:137], v[30:31]
	v_cvt_pk_bf16_f32 v154, v154, v155
	v_cvt_pk_bf16_f32 v155, v156, v157
	v_cvt_pk_bf16_f32 v156, v162, v163
	v_cvt_pk_bf16_f32 v157, v160, v161
	global_store_dwordx4 v[158:159], v[154:157], off
	v_pk_mul_f32 v[160:161], v[152:153], v[24:25]
	v_pk_mul_f32 v[162:163], v[136:137], v[22:23]
	v_pk_mul_f32 v[154:155], v[152:153], v[28:29]
	v_pk_mul_f32 v[156:157], v[136:137], v[26:27]
	v_cvt_pk_bf16_f32 v153, v154, v155
	v_cvt_pk_bf16_f32 v152, v156, v157
	v_cvt_pk_bf16_f32 v154, v162, v163
	v_cvt_pk_bf16_f32 v155, v160, v161
	global_store_dwordx4 v[158:159], v[152:155], off offset:256
	v_pk_mul_f32 v[20:21], v[20:21], v[134:135] op_sel_hi:[1,0]
	v_pk_mul_f32 v[18:19], v[18:19], v[134:135] op_sel_hi:[1,0]
	v_pk_mul_f32 v[12:13], v[12:13], v[134:135] op_sel_hi:[1,0]
	v_pk_mul_f32 v[10:11], v[10:11], v[134:135] op_sel_hi:[1,0]
	v_pk_mul_f32 v[8:9], v[8:9], v[134:135] op_sel_hi:[1,0]
	v_pk_mul_f32 v[6:7], v[6:7], v[134:135] op_sel_hi:[1,0]
	v_pk_mul_f32 v[4:5], v[4:5], v[134:135] op_sel_hi:[1,0]
	v_pk_mul_f32 v[2:3], v[2:3], v[134:135] op_sel_hi:[1,0]
	v_add_u32_e32 v134, 0xb0, v150
	s_and_b64 vcc, exec, s[0:1]
	v_ashrrev_i32_e32 v135, 31, v134
	s_cbranch_vccnz .LBB0_605
	ds_bpermute_b32 v152, v192, v18
	ds_bpermute_b32 v153, v192, v19
	ds_bpermute_b32 v150, v192, v20
	ds_bpermute_b32 v151, v192, v21
	ds_bpermute_b32 v156, v192, v10
	ds_bpermute_b32 v157, v192, v11
	ds_bpermute_b32 v154, v192, v12
	ds_bpermute_b32 v155, v192, v13
	ds_bpermute_b32 v160, v192, v6
	ds_bpermute_b32 v161, v192, v7
	ds_bpermute_b32 v158, v192, v8
	ds_bpermute_b32 v159, v192, v9
	ds_bpermute_b32 v162, v192, v2
	ds_bpermute_b32 v163, v192, v3
	ds_bpermute_b32 v164, v192, v4
	ds_bpermute_b32 v165, v192, v5
	s_and_saveexec_b64 s[0:1], s[6:7]
	s_cbranch_execz .LBB0_604
	s_waitcnt vmcnt(2)
	v_mov_b64_e32 v[166:167], v[218:219]
	v_mov_b64_e32 v[168:169], v[220:221]
	v_mov_b64_e32 v[172:173], v[222:223]
	v_mov_b64_e32 v[174:175], v[224:225]
	v_mov_b64_e32 v[182:183], v[226:227]
	v_mov_b64_e32 v[184:185], v[228:229]
	v_mov_b64_e32 v[186:187], v[230:231]
	v_mov_b64_e32 v[188:189], v[232:233]
	v_xor_b32_e32 v135, 0x80000000, v186
	v_xor_b32_e32 v190, 0x80000000, v187
	v_xor_b32_e32 v191, 0x80000000, v188
	v_xor_b32_e32 v202, 0x80000000, v189
	v_cndmask_b32_e64 v189, v189, v202, s[4:5]
	v_cndmask_b32_e64 v188, v188, v191, s[4:5]
	v_cndmask_b32_e64 v187, v187, v190, s[4:5]
	v_cndmask_b32_e64 v186, v186, v135, s[4:5]
	s_waitcnt lgkmcnt(2)
	v_pk_mul_f32 v[162:163], v[186:187], v[162:163]
	s_waitcnt lgkmcnt(0)
	v_pk_mul_f32 v[164:165], v[188:189], v[164:165]
	v_pk_fma_f32 v[2:3], v[2:3], v[182:183], v[162:163]
	v_pk_fma_f32 v[4:5], v[4:5], v[184:185], v[164:165]
	v_xor_b32_e32 v135, 0x80000000, v172
	v_xor_b32_e32 v164, 0x80000000, v173
	v_xor_b32_e32 v162, 0x80000000, v174
	v_xor_b32_e32 v163, 0x80000000, v175
	v_cndmask_b32_e64 v163, v175, v163, s[4:5]
	v_cndmask_b32_e64 v162, v174, v162, s[4:5]
	v_cndmask_b32_e64 v165, v173, v164, s[4:5]
	v_cndmask_b32_e64 v164, v172, v135, s[4:5]
	v_pk_mul_f32 v[160:161], v[164:165], v[160:161]
	v_pk_mul_f32 v[158:159], v[162:163], v[158:159]
	v_pk_mul_f32 v[156:157], v[186:187], v[156:157]
	v_pk_mul_f32 v[154:155], v[188:189], v[154:155]
	v_pk_mul_f32 v[152:153], v[164:165], v[152:153]
	v_pk_mul_f32 v[150:151], v[162:163], v[150:151]
	v_pk_fma_f32 v[8:9], v[8:9], v[168:169], v[158:159]
	v_pk_fma_f32 v[6:7], v[6:7], v[166:167], v[160:161]
	v_pk_fma_f32 v[12:13], v[12:13], v[184:185], v[154:155]
	v_pk_fma_f32 v[10:11], v[10:11], v[182:183], v[156:157]
	v_pk_fma_f32 v[20:21], v[20:21], v[168:169], v[150:151]
	v_pk_fma_f32 v[18:19], v[18:19], v[166:167], v[152:153]
